# NA epilogue: gate loads and output stores remapped to whole 128-B rows via per-wave LDS transposes (64 line accesses per item instead of 512)
# speedup vs baseline: 1.0339x; 1.0042x over previous
; __device__ __forceinline__ unsigned cvt_pk(float lo, float hi) { f32x2_t v = {lo, hi}; bf16x2_t b = __builtin_convertvector(v, bf16x2_t); return __builtin_bit_cast(unsigned, b); }
; __device__ __forceinline__ float bflo(unsigned u) { return __uint_as_float(u << 16); }
; __device__ __forceinline__ float bfhi(unsigned u) { return __uint_as_float(u & 0xffff0000u); }
; __device__ __forceinline__ float shx(float v, int lane, int m) { return __int_as_float(__builtin_amdgcn_ds_bpermute((lane ^ m) << 2, __float_as_int(v))); }
; __device__ __forceinline__ void na_item(const bf16_t* __restrict__ PMIX, const bf16_t* __restrict__ GP, bf16_t* __restrict__ O, const float* __restrict__ bias, int item, int lane, LAS unsigned char* wl) {
;     ...
;     const float inv = __builtin_amdgcn_rcpf(l + shx(l, lane, 32));
;     const size_t ob = (size_t)qrow * 3072 + 1024 + h * 64;
; #pragma unroll
;     for (int db = 0; db < 2; ++db)
; #pragma unroll
;         for (int g = 0; g < 4; ++g) {
;             const int d = 32 * db + 8 * g + 4 * hi;
;             const u32x2 gw = *reinterpret_cast<const u32x2*>(GP + ob + d);
;             float v0, v1, v2, v3;
;             if (db == 0) { v0 = oT0[4 * g]; v1 = oT0[4 * g + 1]; v2 = oT0[4 * g + 2]; v3 = oT0[4 * g + 3]; } else { v0 = oT1[4 * g]; v1 = oT1[4 * g + 1]; v2 = oT1[4 * g + 2]; v3 = oT1[4 * g + 3]; }
;             u32x2 w; w.x = cvt_pk(v0 * inv * bflo(gw.x), v1 * inv * bfhi(gw.x)); w.y = cvt_pk(v2 * inv * bflo(gw.y), v3 * inv * bfhi(gw.y));
;             *reinterpret_cast<u32x2*>(O + ob + d) = w;
;         }
.LBB0_595:
	s_movk_i32 s66, 0xc00
	v_mad_i64_i32 v[34:35], s[0:1], v187, s66, 0
	v_or_b32_e32 v34, s85, v34
	v_mov_b64_e32 v[36:37], 0x800
	v_lshl_add_u64 v[36:37], v[34:35], 1, v[36:37]
	v_lshl_add_u64 v[34:35], v[144:145], 0, v[36:37]
	s_nop 0
	ds_bpermute_b32 v32, v169, v232
	s_add_i32 s78, s78, s80
	v_readlane_b32 s62, v255, 24
	v_readlane_b32 s38, v255, 26
	v_readlane_b32 s36, v255, 28
	s_waitcnt lgkmcnt(0)
	v_add_f32_e32 v32, v232, v32
	v_rcp_f32_e32 v32, v32
	v_readlane_b32 s42, v255, 30
	s_cmp_ge_i32 s78, s79
	v_readlane_b32 s0, v254, 34
	v_pk_mul_f32 v[16:17], v[16:17], v[32:33] op_sel_hi:[1,0]
	v_pk_mul_f32 v[20:21], v[20:21], v[32:33] op_sel_hi:[1,0]
	v_pk_mul_f32 v[0:1], v[0:1], v[32:33] op_sel_hi:[1,0]
	v_pk_mul_f32 v[2:3], v[2:3], v[32:33] op_sel_hi:[1,0]
	v_readlane_b32 s63, v255, 25
	v_readlane_b32 s39, v255, 27
	v_readlane_b32 s37, v255, 29
	v_readlane_b32 s43, v255, 31
	s_movk_i32 s93, 0x100
	s_mov_b32 s61, 0x800000
	s_movk_i32 s64, 0x3000
	s_movk_i32 s65, 0x7e0
	v_readlane_b32 s1, v254, 35
	v_readlane_b32 s2, v254, 36
	v_readlane_b32 s3, v254, 37
	v_readlane_b32 s4, v254, 38
	v_readlane_b32 s5, v254, 39
	v_readlane_b32 s6, v254, 40
	v_readlane_b32 s7, v254, 41
	v_readlane_b32 s8, v254, 42
	v_readlane_b32 s9, v254, 43
	v_readlane_b32 s10, v254, 44
	v_readlane_b32 s11, v254, 45
	v_readlane_b32 s12, v254, 46
	v_readlane_b32 s13, v254, 47
	v_readlane_b32 s14, v254, 48
	v_readlane_b32 s15, v254, 49
	v_pk_mul_f32 v[18:19], v[18:19], v[32:33] op_sel_hi:[1,0]
	v_pk_mul_f32 v[22:23], v[22:23], v[32:33] op_sel_hi:[1,0]
	v_pk_mul_f32 v[24:25], v[24:25], v[32:33] op_sel_hi:[1,0]
	v_pk_mul_f32 v[26:27], v[26:27], v[32:33] op_sel_hi:[1,0]
	v_pk_mul_f32 v[28:29], v[28:29], v[32:33] op_sel_hi:[1,0]
	v_pk_mul_f32 v[30:31], v[30:31], v[32:33] op_sel_hi:[1,0]
	v_pk_mul_f32 v[4:5], v[4:5], v[32:33] op_sel_hi:[1,0]
	v_pk_mul_f32 v[6:7], v[6:7], v[32:33] op_sel_hi:[1,0]
	v_pk_mul_f32 v[8:9], v[8:9], v[32:33] op_sel_hi:[1,0]
	v_pk_mul_f32 v[10:11], v[10:11], v[32:33] op_sel_hi:[1,0]
	v_pk_mul_f32 v[12:13], v[12:13], v[32:33] op_sel_hi:[1,0]
	v_pk_mul_f32 v[14:15], v[14:15], v[32:33] op_sel_hi:[1,0]
	v_sub_u32_e32 v46, v167, v164
	v_lshlrev_b32_e32 v46, 1, v46
	v_mad_i32_i24 v46, v46, s66, v36
	v_add_u32_e32 v46, v46, v194
	v_lshlrev_b32_e32 v45, 1, v168
	v_sub_u32_e32 v46, v46, v45
	v_mov_b32_e32 v47, 0
	v_sub_u32_e32 v44, v185, v45
	s_mov_b64 s[98:99], 0xc000
	v_lshl_add_u64 v[48:49], v[144:145], 0, v[46:47]
	v_lshl_add_u64 v[50:51], v[48:49], 0, s[98:99]
	v_lshl_add_u64 v[52:53], v[50:51], 0, s[98:99]
	v_lshl_add_u64 v[54:55], v[52:53], 0, s[98:99]
	global_load_dwordx4 v[104:107], v[48:49], off
	global_load_dwordx4 v[108:111], v[50:51], off
	global_load_dwordx4 v[112:115], v[52:53], off
	global_load_dwordx4 v[116:119], v[54:55], off
	v_lshl_add_u64 v[48:49], v[146:147], 0, v[46:47]
	v_lshl_add_u64 v[50:51], v[48:49], 0, s[98:99]
	v_lshl_add_u64 v[52:53], v[50:51], 0, s[98:99]
	v_lshl_add_u64 v[54:55], v[52:53], 0, s[98:99]
	s_mov_b64 s[98:99], 0x14000
	s_waitcnt vmcnt(3)
	ds_write_b128 v184, v[104:107] offset:46080
	s_waitcnt vmcnt(2)
	ds_write_b128 v184, v[108:111] offset:47232
	s_waitcnt vmcnt(1)
	ds_write_b128 v184, v[112:115] offset:48384
	s_waitcnt vmcnt(0)
	ds_write_b128 v184, v[116:119] offset:49536
	s_waitcnt lgkmcnt(0)
	ds_read_b64 v[104:105], v44 offset:46080
	ds_read_b64 v[106:107], v44 offset:46096
	ds_read_b64 v[108:109], v44 offset:46112
	ds_read_b64 v[110:111], v44 offset:46128
	ds_read_b64 v[112:113], v44 offset:46144
	ds_read_b64 v[114:115], v44 offset:46160
	ds_read_b64 v[116:117], v44 offset:46176
	ds_read_b64 v[118:119], v44 offset:46192
	s_waitcnt lgkmcnt(7)
	v_lshlrev_b32_e32 v56, 16, v104
	v_and_b32_e32 v57, 0xffff0000, v104
	v_lshlrev_b32_e32 v58, 16, v105
	v_and_b32_e32 v59, 0xffff0000, v105
	v_pk_mul_f32 v[16:17], v[16:17], v[56:57]
	v_pk_mul_f32 v[18:19], v[18:19], v[58:59]
	s_nop 0
	v_cvt_pk_bf16_f32 v16, v16, v17
	v_cvt_pk_bf16_f32 v17, v18, v19
	s_waitcnt lgkmcnt(6)
	v_lshlrev_b32_e32 v56, 16, v106
	v_and_b32_e32 v57, 0xffff0000, v106
	v_lshlrev_b32_e32 v58, 16, v107
	v_and_b32_e32 v59, 0xffff0000, v107
	v_pk_mul_f32 v[20:21], v[20:21], v[56:57]
	v_pk_mul_f32 v[22:23], v[22:23], v[58:59]
	s_nop 0
	v_cvt_pk_bf16_f32 v20, v20, v21
	v_cvt_pk_bf16_f32 v21, v22, v23
	s_waitcnt lgkmcnt(5)
	v_lshlrev_b32_e32 v56, 16, v108
	v_and_b32_e32 v57, 0xffff0000, v108
	v_lshlrev_b32_e32 v58, 16, v109
	v_and_b32_e32 v59, 0xffff0000, v109
	v_pk_mul_f32 v[24:25], v[24:25], v[56:57]
	v_pk_mul_f32 v[26:27], v[26:27], v[58:59]
	s_nop 0
	v_cvt_pk_bf16_f32 v24, v24, v25
	v_cvt_pk_bf16_f32 v25, v26, v27
	s_waitcnt lgkmcnt(4)
	v_lshlrev_b32_e32 v56, 16, v110
	v_and_b32_e32 v57, 0xffff0000, v110
	v_lshlrev_b32_e32 v58, 16, v111
	v_and_b32_e32 v59, 0xffff0000, v111
	v_pk_mul_f32 v[28:29], v[28:29], v[56:57]
	v_pk_mul_f32 v[30:31], v[30:31], v[58:59]
	s_nop 0
	v_cvt_pk_bf16_f32 v28, v28, v29
	v_cvt_pk_bf16_f32 v29, v30, v31
	s_waitcnt lgkmcnt(3)
	v_lshlrev_b32_e32 v56, 16, v112
	v_and_b32_e32 v57, 0xffff0000, v112
	v_lshlrev_b32_e32 v58, 16, v113
	v_and_b32_e32 v59, 0xffff0000, v113
	v_pk_mul_f32 v[0:1], v[0:1], v[56:57]
	v_pk_mul_f32 v[2:3], v[2:3], v[58:59]
	s_nop 0
	v_cvt_pk_bf16_f32 v0, v0, v1
	v_cvt_pk_bf16_f32 v1, v2, v3
	s_waitcnt lgkmcnt(2)
	v_lshlrev_b32_e32 v56, 16, v114
	v_and_b32_e32 v57, 0xffff0000, v114
	v_lshlrev_b32_e32 v58, 16, v115
	v_and_b32_e32 v59, 0xffff0000, v115
	v_pk_mul_f32 v[4:5], v[4:5], v[56:57]
	v_pk_mul_f32 v[6:7], v[6:7], v[58:59]
	s_nop 0
	v_cvt_pk_bf16_f32 v4, v4, v5
	v_cvt_pk_bf16_f32 v5, v6, v7
	s_waitcnt lgkmcnt(1)
	v_lshlrev_b32_e32 v56, 16, v116
	v_and_b32_e32 v57, 0xffff0000, v116
	v_lshlrev_b32_e32 v58, 16, v117
	v_and_b32_e32 v59, 0xffff0000, v117
	v_pk_mul_f32 v[8:9], v[8:9], v[56:57]
	v_pk_mul_f32 v[10:11], v[10:11], v[58:59]
	s_nop 0
	v_cvt_pk_bf16_f32 v8, v8, v9
	v_cvt_pk_bf16_f32 v9, v10, v11
	s_waitcnt lgkmcnt(0)
	v_lshlrev_b32_e32 v56, 16, v118
	v_and_b32_e32 v57, 0xffff0000, v118
	v_lshlrev_b32_e32 v58, 16, v119
	v_and_b32_e32 v59, 0xffff0000, v119
	v_pk_mul_f32 v[12:13], v[12:13], v[56:57]
	v_pk_mul_f32 v[14:15], v[14:15], v[58:59]
	s_nop 0
	v_cvt_pk_bf16_f32 v12, v12, v13
	v_cvt_pk_bf16_f32 v13, v14, v15
	ds_write_b64 v44, v[16:17]
	ds_write_b64 v44, v[20:21] offset:16
	ds_write_b64 v44, v[24:25] offset:32
	ds_write_b64 v44, v[28:29] offset:48
	ds_write_b64 v44, v[0:1] offset:64
	ds_write_b64 v44, v[4:5] offset:80
	ds_write_b64 v44, v[8:9] offset:96
	ds_write_b64 v44, v[12:13] offset:112
	s_waitcnt lgkmcnt(0)
	ds_read_b128 v[104:107], v184
	ds_read_b128 v[108:111], v184 offset:1152
	ds_read_b128 v[112:115], v184 offset:2304
	ds_read_b128 v[116:119], v184 offset:3456
	s_waitcnt lgkmcnt(3)
	global_store_dwordx4 v[48:49], v[104:107], off
	s_waitcnt lgkmcnt(2)
	global_store_dwordx4 v[50:51], v[108:111], off
	s_waitcnt lgkmcnt(1)
	global_store_dwordx4 v[52:53], v[112:115], off
	s_waitcnt lgkmcnt(0)
	global_store_dwordx4 v[54:55], v[116:119], off
	s_cbranch_scc1 .LBB0_625
